# in-proj epilogue row-stat loads replaced by an LDS-DMA prefetch issued in the last K-iteration + ds_read (on top of DPP/final-norm/FFN-up merge)
# speedup vs baseline: 1.0098x; 1.0025x over previous
.LBB0_293:
	s_cmp_eq_u32 s57, 28
	s_cselect_b32 s42, s10, s19
	s_cselect_b32 s43, s11, s54
	s_cselect_b32 s40, s26, s55
	s_cselect_b32 s41, s27, s56
	s_cbranch_scc0 .Lip_nopf
	s_lshl_b32 s58, s29, 13
	s_add_u32 s58, s14, s58
	s_addc_u32 s59, s15, 0
	v_mbcnt_lo_u32_b32 v250, -1, 0
	v_mbcnt_hi_u32_b32 v250, -1, v250
	v_lshl_add_u32 v250, v250, 4, s46
	s_add_i32 m0, s46, 0x24f80
	s_nop 0
	global_load_lds_dwordx4 v250, s[58:59]
.Lip_nopf:
	s_add_u32 s38, s42, 0x80
	s_addc_u32 s39, s43, 0
	s_add_i32 s60, 0, 0x10000
	s_add_i32 s61, 0, 0x14000
	v_add_u32_e32 v70, s60, v207
	v_add_u32_e32 v110, s61, v207
	ds_read_b128 v[42:45], v70
	ds_read_b128 v[46:49], v70 offset:1024
	ds_read_b128 v[66:69], v70 offset:2048
	ds_read_b128 v[70:73], v70 offset:3072
	ds_read_b128 v[86:89], v110
	ds_read_b128 v[90:93], v110 offset:1024
	ds_read_b128 v[106:109], v110 offset:2048
	ds_read_b128 v[110:113], v110 offset:3072
	s_add_u32 s58, s19, 0x7ff80
	s_addc_u32 s59, s54, 0
	ds_read_b128 v[130:133], v237
	ds_read_b128 v[134:137], v237 offset:1024
	ds_read_b128 v[154:157], v237 offset:2048
	ds_read_b128 v[158:161], v237 offset:3072
	ds_read_b128 v[178:181], v237 offset:4096
	ds_read_b128 v[182:185], v237 offset:5120
	ds_read_b128 v[186:189], v237 offset:6144
	ds_read_b128 v[190:193], v237 offset:7168
	s_add_i32 m0, s46, 0xc000
	v_lshl_add_u64 v[194:195], s[58:59], 0, v[208:209]
	s_add_u32 s58, s58, 0x40000
	s_addc_u32 s59, s59, 0
	global_load_lds_dwordx4 v[194:195], off
	s_add_i32 m0, s46, 0xe000
	v_lshl_add_u64 v[194:195], s[58:59], 0, v[208:209]
	global_load_lds_dwordx4 v[194:195], off
	s_waitcnt vmcnt(8)
	s_waitcnt lgkmcnt(0)
	s_barrier
	s_setprio 1
	s_waitcnt lgkmcnt(0)
	v_mfma_f32_16x16x32_bf16 v[174:177], v[42:45], v[130:133], v[174:177]
	v_mfma_f32_16x16x32_bf16 v[170:173], v[66:69], v[130:133], v[170:173]
	v_mfma_f32_16x16x32_bf16 v[150:153], v[42:45], v[154:157], v[150:153]
	v_mfma_f32_16x16x32_bf16 v[146:149], v[66:69], v[154:157], v[146:149]
	v_mfma_f32_16x16x32_bf16 v[126:129], v[42:45], v[178:181], v[126:129]
	v_mfma_f32_16x16x32_bf16 v[122:125], v[66:69], v[178:181], v[122:125]
	v_mfma_f32_16x16x32_bf16 v[102:105], v[42:45], v[186:189], v[102:105]
	v_mfma_f32_16x16x32_bf16 v[98:101], v[66:69], v[186:189], v[98:101]
	v_mfma_f32_16x16x32_bf16 v[174:177], v[46:49], v[134:137], v[174:177]
	v_mfma_f32_16x16x32_bf16 v[170:173], v[70:73], v[134:137], v[170:173]
	v_mfma_f32_16x16x32_bf16 v[150:153], v[46:49], v[158:161], v[150:153]
	v_mfma_f32_16x16x32_bf16 v[146:149], v[70:73], v[158:161], v[146:149]
	v_mfma_f32_16x16x32_bf16 v[126:129], v[46:49], v[182:185], v[126:129]
	v_mfma_f32_16x16x32_bf16 v[122:125], v[70:73], v[182:185], v[122:125]
	v_mfma_f32_16x16x32_bf16 v[102:105], v[46:49], v[190:193], v[102:105]
	v_mfma_f32_16x16x32_bf16 v[98:101], v[70:73], v[190:193], v[98:101]
	s_setprio 0
	s_setprio 1
	v_mfma_f32_16x16x32_bf16 v[166:169], v[86:89], v[130:133], v[166:169]
	v_mfma_f32_16x16x32_bf16 v[130:133], v[106:109], v[130:133], v[162:165]
	v_mfma_f32_16x16x32_bf16 v[138:141], v[106:109], v[154:157], v[138:141]
	v_mfma_f32_16x16x32_bf16 v[118:121], v[86:89], v[178:181], v[118:121]
	v_mfma_f32_16x16x32_bf16 v[114:117], v[106:109], v[178:181], v[114:117]
	v_mfma_f32_16x16x32_bf16 v[94:97], v[86:89], v[186:189], v[94:97]
	v_mfma_f32_16x16x32_bf16 v[82:85], v[106:109], v[186:189], v[82:85]
	v_mfma_f32_16x16x32_bf16 v[166:169], v[90:93], v[134:137], v[166:169]
	v_mfma_f32_16x16x32_bf16 v[130:133], v[110:113], v[134:137], v[130:133]
	v_mfma_f32_16x16x32_bf16 v[134:137], v[86:89], v[154:157], v[142:145]
	v_mfma_f32_16x16x32_bf16 v[138:141], v[110:113], v[158:161], v[138:141]
	v_mfma_f32_16x16x32_bf16 v[118:121], v[90:93], v[182:185], v[118:121]
	v_mfma_f32_16x16x32_bf16 v[114:117], v[110:113], v[182:185], v[114:117]
	v_mfma_f32_16x16x32_bf16 v[94:97], v[90:93], v[190:193], v[94:97]
	v_mfma_f32_16x16x32_bf16 v[82:85], v[110:113], v[190:193], v[82:85]
	v_mfma_f32_16x16x32_bf16 v[134:137], v[90:93], v[158:161], v[134:137]
	s_setprio 0
	s_barrier
	s_mov_b64 s[58:59], s[40:41]
	ds_read_b128 v[142:145], v237 offset:16384
	ds_read_b128 v[154:157], v237 offset:17408
	ds_read_b128 v[158:161], v237 offset:18432
	ds_read_b128 v[162:165], v237 offset:19456
	ds_read_b128 v[178:181], v237 offset:20480
	ds_read_b128 v[182:185], v237 offset:21504
	ds_read_b128 v[186:189], v237 offset:22528
	ds_read_b128 v[190:193], v237 offset:23552
	s_add_i32 s60, s60, s45
	v_lshl_add_u64 v[194:195], s[58:59], 0, v[202:203]
	s_add_u32 s58, s58, 0x40000
	s_mov_b32 m0, s60
	s_addc_u32 s59, s59, 0
	global_load_lds_dwordx4 v[194:195], off
	s_add_i32 m0, s60, 0x2000
	v_lshl_add_u64 v[194:195], s[58:59], 0, v[202:203]
	s_add_u32 s58, s40, 0x80000
	s_addc_u32 s59, s41, 0
	global_load_lds_dwordx4 v[194:195], off
	s_add_i32 s60, s61, s45
	v_lshl_add_u64 v[194:195], s[58:59], 0, v[202:203]
	s_add_u32 s58, s58, 0x40000
	s_mov_b32 m0, s60
	s_addc_u32 s59, s59, 0
	global_load_lds_dwordx4 v[194:195], off
	s_add_i32 m0, s60, 0x2000
	v_lshl_add_u64 v[194:195], s[58:59], 0, v[202:203]
	s_mov_b64 s[58:59], s[42:43]
	global_load_lds_dwordx4 v[194:195], off
	s_mov_b32 m0, s46
	v_lshl_add_u64 v[194:195], s[58:59], 0, v[208:209]
	s_add_u32 s58, s58, 0x40000
	s_addc_u32 s59, s59, 0
	global_load_lds_dwordx4 v[194:195], off
	s_mov_b32 m0, s47
	v_lshl_add_u64 v[194:195], s[58:59], 0, v[208:209]
	global_load_lds_dwordx4 v[194:195], off
	s_waitcnt vmcnt(8)
	s_waitcnt lgkmcnt(0)
	s_barrier
	s_setprio 1
	s_waitcnt lgkmcnt(0)
	v_mfma_f32_16x16x32_bf16 v[78:81], v[42:45], v[142:145], v[78:81]
	v_mfma_f32_16x16x32_bf16 v[74:77], v[66:69], v[142:145], v[74:77]
	v_mfma_f32_16x16x32_bf16 v[54:57], v[42:45], v[158:161], v[54:57]
	v_mfma_f32_16x16x32_bf16 v[50:53], v[66:69], v[158:161], v[50:53]
	v_mfma_f32_16x16x32_bf16 v[30:33], v[42:45], v[178:181], v[30:33]
	v_mfma_f32_16x16x32_bf16 v[26:29], v[66:69], v[178:181], v[26:29]
	v_mfma_f32_16x16x32_bf16 v[14:17], v[42:45], v[186:189], v[14:17]
	v_mfma_f32_16x16x32_bf16 v[10:13], v[66:69], v[186:189], v[10:13]
	v_mfma_f32_16x16x32_bf16 v[78:81], v[46:49], v[154:157], v[78:81]
	v_mfma_f32_16x16x32_bf16 v[74:77], v[70:73], v[154:157], v[74:77]
	v_mfma_f32_16x16x32_bf16 v[54:57], v[46:49], v[162:165], v[54:57]
	v_mfma_f32_16x16x32_bf16 v[50:53], v[70:73], v[162:165], v[50:53]
	v_mfma_f32_16x16x32_bf16 v[30:33], v[46:49], v[182:185], v[30:33]
	v_mfma_f32_16x16x32_bf16 v[26:29], v[70:73], v[182:185], v[26:29]
	v_mfma_f32_16x16x32_bf16 v[14:17], v[46:49], v[190:193], v[14:17]
	v_mfma_f32_16x16x32_bf16 v[10:13], v[70:73], v[190:193], v[10:13]
	s_setprio 0
	s_setprio 1
	v_mfma_f32_16x16x32_bf16 v[38:41], v[86:89], v[158:161], v[38:41]
	v_mfma_f32_16x16x32_bf16 v[34:37], v[106:109], v[158:161], v[34:37]
	v_mfma_f32_16x16x32_bf16 v[22:25], v[86:89], v[178:181], v[22:25]
	v_mfma_f32_16x16x32_bf16 v[18:21], v[106:109], v[178:181], v[18:21]
	v_mfma_f32_16x16x32_bf16 v[6:9], v[86:89], v[186:189], v[6:9]
	v_mfma_f32_16x16x32_bf16 v[2:5], v[106:109], v[186:189], v[2:5]
	v_mfma_f32_16x16x32_bf16 v[42:45], v[86:89], v[142:145], v[62:65]
	v_mfma_f32_16x16x32_bf16 v[46:49], v[106:109], v[142:145], v[58:61]
	v_mfma_f32_16x16x32_bf16 v[38:41], v[90:93], v[162:165], v[38:41]
	v_mfma_f32_16x16x32_bf16 v[34:37], v[110:113], v[162:165], v[34:37]
	v_mfma_f32_16x16x32_bf16 v[22:25], v[90:93], v[182:185], v[22:25]
	v_mfma_f32_16x16x32_bf16 v[18:21], v[110:113], v[182:185], v[18:21]
	v_mfma_f32_16x16x32_bf16 v[6:9], v[90:93], v[190:193], v[6:9]
	v_mfma_f32_16x16x32_bf16 v[2:5], v[110:113], v[190:193], v[2:5]
	v_mfma_f32_16x16x32_bf16 v[42:45], v[90:93], v[154:157], v[42:45]
	v_mfma_f32_16x16x32_bf16 v[46:49], v[110:113], v[154:157], v[46:49]
	s_setprio 0
	s_barrier
	s_add_i32 s58, 0, 0x18000
	s_add_i32 s59, 0, 0x1c000
	v_add_u32_e32 v70, s58, v207
	v_add_u32_e32 v110, s59, v207
	ds_read_b128 v[58:61], v70
	ds_read_b128 v[62:65], v70 offset:1024
	ds_read_b128 v[66:69], v70 offset:2048
	ds_read_b128 v[70:73], v70 offset:3072
	ds_read_b128 v[86:89], v110
	ds_read_b128 v[90:93], v110 offset:1024
	ds_read_b128 v[106:109], v110 offset:2048
	ds_read_b128 v[110:113], v110 offset:3072
	s_add_u32 s42, s42, 0x80000
	s_addc_u32 s43, s43, 0
	ds_read_b128 v[142:145], v237 offset:32768
	ds_read_b128 v[154:157], v237 offset:33792
	ds_read_b128 v[158:161], v237 offset:34816
	ds_read_b128 v[178:181], v237 offset:35840
	ds_read_b128 v[182:185], v237 offset:36864
	ds_read_b128 v[186:189], v237 offset:37888
	ds_read_b128 v[190:193], v237 offset:38912
	ds_read_b128 v[194:197], v237 offset:39936
	s_mov_b32 m0, s48
	v_lshl_add_u64 v[162:163], s[42:43], 0, v[208:209]
	s_add_u32 s42, s42, 0x40000
	s_addc_u32 s43, s43, 0
	global_load_lds_dwordx4 v[162:163], off
	s_mov_b32 m0, s49
	v_lshl_add_u64 v[162:163], s[42:43], 0, v[208:209]
	global_load_lds_dwordx4 v[162:163], off
	s_waitcnt vmcnt(8)
	s_waitcnt lgkmcnt(0)
	s_barrier
	s_setprio 1
	s_waitcnt lgkmcnt(0)
	v_mfma_f32_16x16x32_bf16 v[162:165], v[58:61], v[142:145], v[174:177]
	v_mfma_f32_16x16x32_bf16 v[174:177], v[62:65], v[154:157], v[162:165]
	v_mfma_f32_16x16x32_bf16 v[162:165], v[66:69], v[142:145], v[170:173]
	v_mfma_f32_16x16x32_bf16 v[150:153], v[58:61], v[158:161], v[150:153]
	v_mfma_f32_16x16x32_bf16 v[146:149], v[66:69], v[158:161], v[146:149]
	v_mfma_f32_16x16x32_bf16 v[126:129], v[58:61], v[182:185], v[126:129]
	v_mfma_f32_16x16x32_bf16 v[122:125], v[66:69], v[182:185], v[122:125]
	v_mfma_f32_16x16x32_bf16 v[102:105], v[58:61], v[190:193], v[102:105]
	v_mfma_f32_16x16x32_bf16 v[98:101], v[66:69], v[190:193], v[98:101]
	v_mfma_f32_16x16x32_bf16 v[170:173], v[70:73], v[154:157], v[162:165]
	v_mfma_f32_16x16x32_bf16 v[150:153], v[62:65], v[178:181], v[150:153]
	v_mfma_f32_16x16x32_bf16 v[146:149], v[70:73], v[178:181], v[146:149]
	v_mfma_f32_16x16x32_bf16 v[126:129], v[62:65], v[186:189], v[126:129]
	v_mfma_f32_16x16x32_bf16 v[122:125], v[70:73], v[186:189], v[122:125]
	v_mfma_f32_16x16x32_bf16 v[102:105], v[62:65], v[194:197], v[102:105]
	v_mfma_f32_16x16x32_bf16 v[98:101], v[70:73], v[194:197], v[98:101]
	s_setprio 0
	s_setprio 1
	v_mfma_f32_16x16x32_bf16 v[162:165], v[86:89], v[142:145], v[166:169]
	v_mfma_f32_16x16x32_bf16 v[130:133], v[106:109], v[142:145], v[130:133]
	v_mfma_f32_16x16x32_bf16 v[166:169], v[90:93], v[154:157], v[162:165]
	v_mfma_f32_16x16x32_bf16 v[162:165], v[110:113], v[154:157], v[130:133]
	v_mfma_f32_16x16x32_bf16 v[130:133], v[86:89], v[158:161], v[134:137]
	v_mfma_f32_16x16x32_bf16 v[142:145], v[90:93], v[178:181], v[130:133]
	v_mfma_f32_16x16x32_bf16 v[130:133], v[106:109], v[158:161], v[138:141]
	v_mfma_f32_16x16x32_bf16 v[118:121], v[86:89], v[182:185], v[118:121]
	v_mfma_f32_16x16x32_bf16 v[114:117], v[106:109], v[182:185], v[114:117]
	v_mfma_f32_16x16x32_bf16 v[94:97], v[86:89], v[190:193], v[94:97]
	v_mfma_f32_16x16x32_bf16 v[82:85], v[106:109], v[190:193], v[82:85]
	v_mfma_f32_16x16x32_bf16 v[138:141], v[110:113], v[178:181], v[130:133]
	v_mfma_f32_16x16x32_bf16 v[118:121], v[90:93], v[186:189], v[118:121]
	v_mfma_f32_16x16x32_bf16 v[114:117], v[110:113], v[186:189], v[114:117]
	v_mfma_f32_16x16x32_bf16 v[94:97], v[90:93], v[194:197], v[94:97]
	v_mfma_f32_16x16x32_bf16 v[82:85], v[110:113], v[194:197], v[82:85]
	s_setprio 0
	s_barrier
	s_add_u32 s42, s40, 0x80
	s_addc_u32 s43, s41, 0
	ds_read_b128 v[130:133], v237 offset:49152
	ds_read_b128 v[134:137], v237 offset:50176
	ds_read_b128 v[154:157], v237 offset:51200
	ds_read_b128 v[158:161], v237 offset:52224
	ds_read_b128 v[178:181], v237 offset:53248
	ds_read_b128 v[182:185], v237 offset:54272
	ds_read_b128 v[186:189], v237 offset:55296
	ds_read_b128 v[190:193], v237 offset:56320
	s_add_i32 s58, s58, s45
	v_lshl_add_u64 v[194:195], s[42:43], 0, v[202:203]
	s_mov_b32 m0, s58
	s_add_u32 s42, s42, 0x40000
	global_load_lds_dwordx4 v[194:195], off
	s_addc_u32 s43, s43, 0
	s_add_i32 m0, s58, 0x2000
	s_add_u32 s40, s40, 0x80080
	s_addc_u32 s41, s41, 0
	v_lshl_add_u64 v[194:195], s[42:43], 0, v[202:203]
	global_load_lds_dwordx4 v[194:195], off
	s_add_i32 s42, s59, s45
	v_lshl_add_u64 v[194:195], s[40:41], 0, v[202:203]
	s_add_u32 s40, s40, 0x40000
	s_mov_b32 m0, s42
	s_addc_u32 s41, s41, 0
	global_load_lds_dwordx4 v[194:195], off
	s_add_i32 m0, s42, 0x2000
	v_lshl_add_u64 v[194:195], s[40:41], 0, v[202:203]
	global_load_lds_dwordx4 v[194:195], off
	s_mov_b32 m0, s50
	v_lshl_add_u64 v[194:195], s[38:39], 0, v[208:209]
	s_add_u32 s38, s38, 0x40000
	s_addc_u32 s39, s39, 0
	global_load_lds_dwordx4 v[194:195], off
	s_mov_b32 m0, s51
	v_lshl_add_u64 v[194:195], s[38:39], 0, v[208:209]
	global_load_lds_dwordx4 v[194:195], off
	s_waitcnt vmcnt(8)
	s_waitcnt lgkmcnt(0)
	s_barrier
	s_setprio 1
	s_waitcnt lgkmcnt(0)
	v_mfma_f32_16x16x32_bf16 v[78:81], v[58:61], v[130:133], v[78:81]
	v_mfma_f32_16x16x32_bf16 v[74:77], v[66:69], v[130:133], v[74:77]
	v_mfma_f32_16x16x32_bf16 v[54:57], v[58:61], v[154:157], v[54:57]
	v_mfma_f32_16x16x32_bf16 v[50:53], v[66:69], v[154:157], v[50:53]
	v_mfma_f32_16x16x32_bf16 v[30:33], v[58:61], v[178:181], v[30:33]
	v_mfma_f32_16x16x32_bf16 v[26:29], v[66:69], v[178:181], v[26:29]
	v_mfma_f32_16x16x32_bf16 v[14:17], v[58:61], v[186:189], v[14:17]
	v_mfma_f32_16x16x32_bf16 v[10:13], v[66:69], v[186:189], v[10:13]
	v_mfma_f32_16x16x32_bf16 v[78:81], v[62:65], v[134:137], v[78:81]
	v_mfma_f32_16x16x32_bf16 v[74:77], v[70:73], v[134:137], v[74:77]
	v_mfma_f32_16x16x32_bf16 v[54:57], v[62:65], v[158:161], v[54:57]
	v_mfma_f32_16x16x32_bf16 v[50:53], v[70:73], v[158:161], v[50:53]
	v_mfma_f32_16x16x32_bf16 v[30:33], v[62:65], v[182:185], v[30:33]
	v_mfma_f32_16x16x32_bf16 v[26:29], v[70:73], v[182:185], v[26:29]
	v_mfma_f32_16x16x32_bf16 v[14:17], v[62:65], v[190:193], v[14:17]
	v_mfma_f32_16x16x32_bf16 v[10:13], v[70:73], v[190:193], v[10:13]
	s_setprio 0
	s_setprio 1
	v_mfma_f32_16x16x32_bf16 v[42:45], v[86:89], v[130:133], v[42:45]
	v_mfma_f32_16x16x32_bf16 v[62:65], v[90:93], v[134:137], v[42:45]
	v_mfma_f32_16x16x32_bf16 v[42:45], v[106:109], v[130:133], v[46:49]
	v_mfma_f32_16x16x32_bf16 v[38:41], v[86:89], v[154:157], v[38:41]
	v_mfma_f32_16x16x32_bf16 v[34:37], v[106:109], v[154:157], v[34:37]
	v_mfma_f32_16x16x32_bf16 v[22:25], v[86:89], v[178:181], v[22:25]
	v_mfma_f32_16x16x32_bf16 v[18:21], v[106:109], v[178:181], v[18:21]
	v_mfma_f32_16x16x32_bf16 v[6:9], v[86:89], v[186:189], v[6:9]
	v_mfma_f32_16x16x32_bf16 v[2:5], v[106:109], v[186:189], v[2:5]
	v_mfma_f32_16x16x32_bf16 v[58:61], v[110:113], v[134:137], v[42:45]
	v_mfma_f32_16x16x32_bf16 v[38:41], v[90:93], v[158:161], v[38:41]
	v_mfma_f32_16x16x32_bf16 v[34:37], v[110:113], v[158:161], v[34:37]
	v_mfma_f32_16x16x32_bf16 v[22:25], v[90:93], v[182:185], v[22:25]
	v_mfma_f32_16x16x32_bf16 v[18:21], v[110:113], v[182:185], v[18:21]
	v_mfma_f32_16x16x32_bf16 v[6:9], v[90:93], v[190:193], v[6:9]
	v_mfma_f32_16x16x32_bf16 v[2:5], v[110:113], v[190:193], v[2:5]
	s_setprio 0
	s_barrier
	s_add_i32 s57, s57, 2
	s_add_u32 s19, s19, 0x100
	s_addc_u32 s54, s54, 0
	s_add_u32 s55, s55, 0x100
	s_addc_u32 s56, s56, 0
	s_cmp_gt_u32 s57, 29
	s_cbranch_scc0 .LBB0_293
	s_and_b64 vcc, exec, s[16:17]
	s_cbranch_vccz .LBB0_296
	s_barrier
.LBB0_296:
	v_lshl_add_u32 v224, s29, 8, v205
	v_lshlrev_b32_e32 v250, 5, v205
	v_add_u32_e32 v250, 0x24f80, v250
	v_ashrrev_i32_e32 v225, 31, v224
	v_or_b32_e32 v222, 16, v224
	v_ashrrev_i32_e32 v223, 31, v222
	ds_read_b128 v[194:197], v250 offset:16
	ds_read_b128 v[198:201], v250 offset:0
	v_or_b32_e32 v220, 32, v224
	v_ashrrev_i32_e32 v221, 31, v220
	ds_read_b128 v[178:181], v250 offset:528
	ds_read_b128 v[182:185], v250 offset:512
	v_or_b32_e32 v218, 48, v224
	v_ashrrev_i32_e32 v219, 31, v218
	ds_read_b128 v[154:157], v250 offset:1040
	ds_read_b128 v[158:161], v250 offset:1024
	v_add_u32_e32 v216, 0x80, v224
	v_ashrrev_i32_e32 v217, 31, v216
	ds_read_b128 v[130:133], v250 offset:1552
	ds_read_b128 v[134:137], v250 offset:1536
	v_add_u32_e32 v214, 0x90, v224
	v_ashrrev_i32_e32 v215, 31, v214
	ds_read_b128 v[106:109], v250 offset:4112
	ds_read_b128 v[110:113], v250 offset:4096
	v_add_u32_e32 v212, 0xa0, v224
	v_ashrrev_i32_e32 v213, 31, v212
	ds_read_b128 v[86:89], v250 offset:4624
	ds_read_b128 v[90:93], v250 offset:4608
	v_add_u32_e32 v210, 0xb0, v224
	v_ashrrev_i32_e32 v211, 31, v210
	ds_read_b128 v[66:69], v250 offset:5136
	ds_read_b128 v[70:73], v250 offset:5120
	ds_read_b128 v[42:45], v250 offset:5648
	ds_read_b128 v[46:49], v250 offset:5632
	s_add_i32 s10, s28, -10
	s_cmp_lt_u32 s10, 4
	s_cselect_b64 s[26:27], -1, 0
	s_cmp_gt_u32 s10, 3
	s_cbranch_scc1 .LBB0_298
	v_lshlrev_b32_e32 v186, 7, v224
	s_mov_b32 s10, 0x3e780
	v_and_or_b32 v186, v186, s10, v236
	v_lshlrev_b32_e32 v190, 2, v186
	global_load_dwordx4 v[186:189], v190, s[8:9] offset:16
	s_nop 0
	global_load_dwordx4 v[190:193], v190, s[8:9]
	s_waitcnt vmcnt(0)
	s_branch .LBB0_299

.LBB0_299:
	s_waitcnt lgkmcnt(0)
	v_add_f32_e32 v198, v198, v199
	v_add_f32_e32 v199, v200, v201
	v_add_f32_e32 v194, v194, v195
	v_add_f32_e32 v195, v196, v197
	v_add_f32_e32 v198, v198, v199
	v_add_f32_e32 v194, v194, v195
	v_add_f32_e32 v194, v198, v194
	v_fmamk_f32 v194, v194, 0x3a000000, v1
	v_rsq_f32_e32 v194, v194
	s_cmp_lt_i32 s28, 4
	s_cselect_b64 s[10:11], -1, 0
	s_cmp_gt_i32 s28, 3
	v_pk_mul_f32 v[176:177], v[176:177], v[194:195] op_sel_hi:[1,0]
	v_pk_mul_f32 v[174:175], v[174:175], v[194:195] op_sel_hi:[1,0]
	v_pk_mul_f32 v[172:173], v[172:173], v[194:195] op_sel_hi:[1,0]
	v_pk_mul_f32 v[170:171], v[170:171], v[194:195] op_sel_hi:[1,0]
	s_mov_b64 s[38:39], -1
	s_cbranch_scc1 .LBB0_301
	v_mul_f32_e32 v196, v170, v170
	v_mul_f32_e32 v195, v174, v174
	v_fmamk_f32 v196, v196, 0xbdd2d3e7, v228
	v_fmamk_f32 v195, v195, 0xbdd2d3e7, v228
	v_mul_f32_e32 v196, v170, v196
	v_mul_f32_e32 v195, v174, v195
	v_exp_f32_e32 v197, v196
	v_mul_f32_e32 v196, v175, v175
	v_exp_f32_e32 v195, v195
	v_fmamk_f32 v196, v196, 0xbdd2d3e7, v228
	v_mul_f32_e32 v196, v175, v196
	v_exp_f32_e32 v198, v196
	v_add_f32_e32 v195, 1.0, v195
	v_mul_f32_e32 v200, v177, v177
	v_rcp_f32_e32 v196, v195
	v_add_f32_e32 v195, 1.0, v197
	v_fmamk_f32 v200, v200, 0xbdd2d3e7, v228
	v_rcp_f32_e32 v226, v195
	v_add_f32_e32 v195, 1.0, v198
	v_mul_f32_e32 v199, v172, v172
	v_mul_f32_e32 v200, v177, v200
	v_rcp_f32_e32 v197, v195
	v_mul_f32_e32 v195, v171, v171
	v_mul_f32_e32 v198, v176, v176
	v_fmamk_f32 v199, v199, 0xbdd2d3e7, v228
	v_exp_f32_e32 v201, v200
	v_mul_f32_e32 v200, v173, v173
	v_fmamk_f32 v195, v195, 0xbdd2d3e7, v228
	v_fmamk_f32 v198, v198, 0xbdd2d3e7, v228
	v_mul_f32_e32 v199, v172, v199
	v_fmamk_f32 v200, v200, 0xbdd2d3e7, v228
	v_mul_f32_e32 v195, v171, v195
	v_mul_f32_e32 v198, v176, v198
	v_exp_f32_e32 v199, v199
	v_mul_f32_e32 v200, v173, v200
	v_exp_f32_e32 v195, v195
	v_exp_f32_e32 v198, v198
	v_exp_f32_e32 v211, v200
	v_add_f32_e32 v199, 1.0, v199
	v_add_f32_e32 v195, 1.0, v195
	v_add_f32_e32 v198, 1.0, v198
	v_rcp_f32_e32 v200, v199
	v_add_f32_e32 v199, 1.0, v201
	v_add_f32_e32 v201, 1.0, v211
	v_rcp_f32_e32 v198, v198
	v_rcp_f32_e32 v199, v199
	v_rcp_f32_e32 v201, v201
	v_rcp_f32_e32 v227, v195
	v_pk_mul_f32 v[196:197], v[174:175], v[196:197]
	v_pk_mul_f32 v[198:199], v[176:177], v[198:199]
	v_pk_mul_f32 v[200:201], v[172:173], v[200:201]
	v_pk_mul_f32 v[226:227], v[170:171], v[226:227]
	s_mov_b64 s[38:39], 0

.LBB0_305:
	v_lshl_or_b32 v170, s28, 8, v236
	v_mov_b64_e32 v[172:173], s[6:7]
	v_ashrrev_i32_e32 v171, 31, v170
	v_mad_i64_i32 v[172:173], s[26:27], v224, s3, v[172:173]
	v_lshl_add_u64 v[172:173], v[170:171], 1, v[172:173]
	v_cvt_pk_bf16_f32 v174, v196, v197
	v_cvt_pk_bf16_f32 v175, v198, v199
	v_cvt_pk_bf16_f32 v176, v226, v227
	v_cvt_pk_bf16_f32 v177, v200, v201
	s_waitcnt vmcnt(0)
	global_store_dwordx4 v[172:173], v[174:177], off
	v_mov_b32_e32 v195, v194
	v_pk_mul_f32 v[166:167], v[166:167], v[194:195]
	v_mov_b32_e32 v174, v194
	v_mov_b32_e32 v175, v194
	v_pk_mul_f32 v[168:169], v[168:169], v[174:175]
	v_pk_mul_f32 v[164:165], v[164:165], v[174:175]
	v_cndmask_b32_e64 v174, 0, 1, s[10:11]
	v_pk_mul_f32 v[162:163], v[162:163], v[194:195]
	v_cmp_ne_u32_e64 s[42:43], 1, v174
	s_andn2_b64 vcc, exec, s[10:11]
	s_mov_b64 s[10:11], -1
	s_cbranch_vccnz .LBB0_307
	v_mul_f32_e32 v175, v162, v162
	v_fmamk_f32 v175, v175, 0xbdd2d3e7, v228
	v_mul_f32_e32 v176, v167, v167
	v_mul_f32_e32 v175, v162, v175
	v_fmamk_f32 v176, v176, 0xbdd2d3e7, v228
	v_exp_f32_e32 v175, v175
	v_mul_f32_e32 v176, v167, v176
	v_exp_f32_e32 v176, v176
	v_mul_f32_e32 v177, v168, v168
	v_add_f32_e32 v175, 1.0, v175
	v_rcp_f32_e32 v196, v175
	v_add_f32_e32 v175, 1.0, v176
	v_mul_f32_e32 v176, v163, v163
	v_mul_f32_e32 v194, v164, v164
	v_fmamk_f32 v176, v176, 0xbdd2d3e7, v228
	v_fmamk_f32 v177, v177, 0xbdd2d3e7, v228
	v_fmamk_f32 v194, v194, 0xbdd2d3e7, v228
	v_mul_f32_e32 v176, v163, v176
	v_mul_f32_e32 v177, v168, v177
	v_mul_f32_e32 v194, v164, v194
	v_exp_f32_e32 v176, v176
	v_exp_f32_e32 v177, v177
	v_exp_f32_e32 v194, v194
	v_mul_f32_e32 v174, v166, v166
	v_add_f32_e32 v197, 1.0, v176
	v_add_f32_e32 v176, 1.0, v177
	v_add_f32_e32 v177, 1.0, v194
	v_mul_f32_e32 v194, v169, v169
	v_fmamk_f32 v194, v194, 0xbdd2d3e7, v228
	v_mul_f32_e32 v194, v169, v194
	v_exp_f32_e32 v195, v194
	v_mul_f32_e32 v194, v165, v165
	v_fmamk_f32 v174, v174, 0xbdd2d3e7, v228
	v_fmamk_f32 v194, v194, 0xbdd2d3e7, v228
	v_mul_f32_e32 v174, v166, v174
	v_mul_f32_e32 v194, v165, v194
	v_exp_f32_e32 v174, v174
	v_exp_f32_e32 v198, v194
	v_rcp_f32_e32 v194, v177
	v_add_f32_e32 v177, 1.0, v195
	v_add_f32_e32 v174, 1.0, v174
	v_add_f32_e32 v195, 1.0, v198
	v_rcp_f32_e32 v174, v174
	v_rcp_f32_e32 v175, v175
	v_rcp_f32_e32 v176, v176
	v_rcp_f32_e32 v177, v177
	v_rcp_f32_e32 v195, v195
	v_rcp_f32_e32 v197, v197
	v_pk_mul_f32 v[174:175], v[166:167], v[174:175]
	v_pk_mul_f32 v[176:177], v[168:169], v[176:177]
	v_pk_mul_f32 v[194:195], v[164:165], v[194:195]
	v_pk_mul_f32 v[196:197], v[162:163], v[196:197]
	s_mov_b64 s[10:11], 0
